# adds counted vmcnt waits (instead of vmcnt(0)) after the last residual refill loads in the bf16-residual epilogues of the down/out GEMMs
# baseline (speedup 1.0000x reference)
.LBB0_312:
	s_or_b64 exec, exec, s[18:19]
	v_or_b32_e32 v72, 48, v120
	v_ashrrev_i32_e32 v73, 31, v72
	s_waitcnt lgkmcnt(0)
	v_lshlrev_b64 v[64:65], 11, v[72:73]
	v_lshl_add_u64 v[64:65], s[26:27], 0, v[64:65]
	v_lshl_add_u64 v[74:75], v[182:183], 1, v[64:65]
	global_load_dwordx4 v[68:71], v[74:75], off
	global_load_dwordx4 v[64:67], v[74:75], off offset:256
	s_waitcnt vmcnt(15)
	v_lshlrev_b32_e32 v76, 16, v116
	v_fmac_f32_e32 v76, 0.5, v60
	v_and_b32_e32 v60, 0xffff0000, v116
	v_fmac_f32_e32 v60, 0.5, v61
	v_lshlrev_b32_e32 v61, 16, v117
	v_fmac_f32_e32 v61, 0.5, v62
	v_and_b32_e32 v62, 0xffff0000, v117
	v_fmac_f32_e32 v62, 0.5, v63
	v_lshlrev_b32_e32 v63, 16, v118
	v_lshlrev_b32_e32 v78, 16, v119
	v_fmac_f32_e32 v63, 0.5, v56
	v_fmac_f32_e32 v78, 0.5, v58
	v_cvt_pk_bf16_f32 v56, v76, v60
	v_mul_f32_e32 v58, v60, v60
	v_lshlrev_b32_e32 v60, 16, v112
	v_fmac_f32_e32 v60, 0.5, v52
	v_and_b32_e32 v52, 0xffff0000, v112
	v_and_b32_e32 v79, 0xffff0000, v119
	v_fmac_f32_e32 v52, 0.5, v53
	v_lshlrev_b32_e32 v53, 16, v113
	v_and_b32_e32 v77, 0xffff0000, v118
	v_fmac_f32_e32 v79, 0.5, v59
	v_mul_f32_e32 v59, v62, v62
	v_fmac_f32_e32 v53, 0.5, v54
	v_and_b32_e32 v54, 0xffff0000, v113
	v_fmac_f32_e32 v77, 0.5, v57
	v_cvt_pk_bf16_f32 v57, v61, v62
	v_fmac_f32_e32 v59, v61, v61
	v_fmac_f32_e32 v54, 0.5, v55
	v_lshlrev_b32_e32 v55, 16, v114
	v_and_b32_e32 v61, 0xffff0000, v114
	v_fmac_f32_e32 v55, 0.5, v48
	v_fmac_f32_e32 v61, 0.5, v49
	v_mul_f32_e32 v48, v52, v52
	v_mul_f32_e32 v49, v54, v54
	v_fmac_f32_e32 v58, v76, v76
	v_fmac_f32_e32 v48, v60, v60
	v_fmac_f32_e32 v49, v53, v53
	v_add_f32_e32 v58, v58, v59
	v_mul_f32_e32 v59, v77, v77
	v_and_b32_e32 v76, 0xffff0000, v115
	v_add_f32_e32 v48, v48, v49
	v_mul_f32_e32 v49, v61, v61
	v_fmac_f32_e32 v59, v63, v63
	v_lshlrev_b32_e32 v62, 16, v115
	v_fmac_f32_e32 v76, 0.5, v51
	v_fmac_f32_e32 v49, v55, v55
	v_add_f32_e32 v58, v59, v58
	v_mul_f32_e32 v59, v79, v79
	v_fmac_f32_e32 v62, 0.5, v50
	v_add_f32_e32 v48, v49, v48
	v_mul_f32_e32 v49, v76, v76
	v_fmac_f32_e32 v59, v78, v78
	v_fmac_f32_e32 v49, v62, v62
	v_add_f32_e32 v58, v59, v58
	v_add_f32_e32 v48, v49, v48
	v_add_f32_e32 v48, v58, v48
	ds_bpermute_b32 v49, v124, v48
	v_cvt_pk_bf16_f32 v58, v63, v77
	v_cvt_pk_bf16_f32 v59, v78, v79
	global_store_dwordx4 v[122:123], v[56:59], off
	v_cvt_pk_bf16_f32 v50, v60, v52
	s_waitcnt lgkmcnt(0)
	v_add_f32_e32 v48, v48, v49
	ds_bpermute_b32 v49, v125, v48
	v_cvt_pk_bf16_f32 v51, v53, v54
	v_cvt_pk_bf16_f32 v52, v55, v61
	v_cvt_pk_bf16_f32 v53, v62, v76
	global_store_dwordx4 v[122:123], v[50:53], off offset:256
	s_and_saveexec_b64 s[18:19], s[46:47]
	s_cbranch_execz .LBB0_314
	v_lshlrev_b64 v[50:51], 6, v[120:121]
	v_lshl_add_u64 v[50:51], s[28:29], 0, v[50:51]
	v_lshl_add_u64 v[50:51], s[60:61], 2, v[50:51]
	s_lshl_b32 s8, s78, 2
	v_lshl_add_u64 v[50:51], v[50:51], 0, s[8:9]
	s_waitcnt lgkmcnt(0)
	v_add_f32_e32 v48, v48, v49
	flat_store_dword v[50:51], v48
.LBB0_314:
	s_or_b64 exec, exec, s[18:19]
	s_waitcnt vmcnt(13)
	v_lshlrev_b32_e32 v48, 16, v100
	v_fmac_f32_e32 v48, 0.5, v44
	v_and_b32_e32 v44, 0xffff0000, v100
	v_fmac_f32_e32 v44, 0.5, v45
	v_lshlrev_b32_e32 v45, 16, v101
	v_fmac_f32_e32 v45, 0.5, v46
	v_and_b32_e32 v46, 0xffff0000, v101
	v_fmac_f32_e32 v46, 0.5, v47
	v_lshlrev_b32_e32 v47, 16, v102
	v_lshlrev_b32_e32 v50, 16, v103
	v_fmac_f32_e32 v47, 0.5, v40
	v_fmac_f32_e32 v50, 0.5, v42
	v_cvt_pk_bf16_f32 v40, v48, v44
	v_mul_f32_e32 v42, v44, v44
	v_lshlrev_b32_e32 v44, 16, v96
	v_fmac_f32_e32 v44, 0.5, v36
	v_and_b32_e32 v36, 0xffff0000, v96
	v_and_b32_e32 v51, 0xffff0000, v103
	v_fmac_f32_e32 v36, 0.5, v37
	v_lshlrev_b32_e32 v37, 16, v97
	s_waitcnt lgkmcnt(0)
	v_and_b32_e32 v49, 0xffff0000, v102
	v_fmac_f32_e32 v51, 0.5, v43
	v_mul_f32_e32 v43, v46, v46
	v_fmac_f32_e32 v37, 0.5, v38
	v_and_b32_e32 v38, 0xffff0000, v97
	v_fmac_f32_e32 v49, 0.5, v41
	v_cvt_pk_bf16_f32 v41, v45, v46
	v_fmac_f32_e32 v43, v45, v45
	v_fmac_f32_e32 v38, 0.5, v39
	v_lshlrev_b32_e32 v39, 16, v98
	v_and_b32_e32 v45, 0xffff0000, v98
	v_fmac_f32_e32 v39, 0.5, v32
	v_fmac_f32_e32 v45, 0.5, v33
	v_mul_f32_e32 v32, v36, v36
	v_mul_f32_e32 v33, v38, v38
	v_fmac_f32_e32 v42, v48, v48
	v_fmac_f32_e32 v32, v44, v44
	v_fmac_f32_e32 v33, v37, v37
	v_add_f32_e32 v42, v42, v43
	v_mul_f32_e32 v43, v49, v49
	v_and_b32_e32 v48, 0xffff0000, v99
	v_add_f32_e32 v32, v32, v33
	v_mul_f32_e32 v33, v45, v45
	v_fmac_f32_e32 v43, v47, v47
	v_lshlrev_b32_e32 v46, 16, v99
	v_fmac_f32_e32 v48, 0.5, v35
	v_fmac_f32_e32 v33, v39, v39
	v_add_f32_e32 v42, v43, v42
	v_mul_f32_e32 v43, v51, v51
	v_fmac_f32_e32 v46, 0.5, v34
	v_add_f32_e32 v32, v33, v32
	v_mul_f32_e32 v33, v48, v48
	v_fmac_f32_e32 v43, v50, v50
	v_fmac_f32_e32 v33, v46, v46
	v_add_f32_e32 v42, v43, v42
	v_add_f32_e32 v32, v33, v32
	v_add_f32_e32 v32, v42, v32
	ds_bpermute_b32 v33, v124, v32
	v_cvt_pk_bf16_f32 v42, v47, v49
	v_cvt_pk_bf16_f32 v43, v50, v51
	global_store_dwordx4 v[106:107], v[40:43], off
	v_cvt_pk_bf16_f32 v34, v44, v36
	s_waitcnt lgkmcnt(0)
	v_add_f32_e32 v32, v32, v33
	ds_bpermute_b32 v33, v125, v32
	v_cvt_pk_bf16_f32 v35, v37, v38
	v_cvt_pk_bf16_f32 v36, v39, v45
	v_cvt_pk_bf16_f32 v37, v46, v48
	global_store_dwordx4 v[106:107], v[34:37], off offset:256
	s_and_saveexec_b64 s[18:19], s[46:47]
	s_cbranch_execz .LBB0_316
	v_lshlrev_b64 v[34:35], 6, v[104:105]
	v_lshl_add_u64 v[34:35], s[28:29], 0, v[34:35]
	v_lshl_add_u64 v[34:35], s[60:61], 2, v[34:35]
	s_lshl_b32 s8, s78, 2
	v_lshl_add_u64 v[34:35], v[34:35], 0, s[8:9]
	s_waitcnt lgkmcnt(0)
	v_add_f32_e32 v32, v32, v33
	flat_store_dword v[34:35], v32
.LBB0_316:
	s_or_b64 exec, exec, s[18:19]
	s_waitcnt vmcnt(11)
	v_lshlrev_b32_e32 v32, 16, v84
	v_fmac_f32_e32 v32, 0.5, v28
	v_and_b32_e32 v28, 0xffff0000, v84
	v_fmac_f32_e32 v28, 0.5, v29
	v_lshlrev_b32_e32 v29, 16, v85
	v_fmac_f32_e32 v29, 0.5, v30
	v_and_b32_e32 v30, 0xffff0000, v85
	v_fmac_f32_e32 v30, 0.5, v31
	v_lshlrev_b32_e32 v31, 16, v86
	v_lshlrev_b32_e32 v34, 16, v87
	v_fmac_f32_e32 v31, 0.5, v24
	v_fmac_f32_e32 v34, 0.5, v26
	v_cvt_pk_bf16_f32 v24, v32, v28
	v_mul_f32_e32 v26, v28, v28
	v_lshlrev_b32_e32 v28, 16, v80
	v_fmac_f32_e32 v28, 0.5, v20
	v_and_b32_e32 v20, 0xffff0000, v80
	v_and_b32_e32 v35, 0xffff0000, v87
	v_fmac_f32_e32 v20, 0.5, v21
	v_lshlrev_b32_e32 v21, 16, v81
	s_waitcnt lgkmcnt(0)
	v_and_b32_e32 v33, 0xffff0000, v86
	v_fmac_f32_e32 v35, 0.5, v27
	v_mul_f32_e32 v27, v30, v30
	v_fmac_f32_e32 v21, 0.5, v22
	v_and_b32_e32 v22, 0xffff0000, v81
	v_fmac_f32_e32 v33, 0.5, v25
	v_cvt_pk_bf16_f32 v25, v29, v30
	v_fmac_f32_e32 v27, v29, v29
	v_fmac_f32_e32 v22, 0.5, v23
	v_lshlrev_b32_e32 v23, 16, v82
	v_and_b32_e32 v29, 0xffff0000, v82
	v_fmac_f32_e32 v23, 0.5, v16
	v_fmac_f32_e32 v29, 0.5, v17
	v_mul_f32_e32 v16, v20, v20
	v_mul_f32_e32 v17, v22, v22
	v_fmac_f32_e32 v26, v32, v32
	v_fmac_f32_e32 v16, v28, v28
	v_fmac_f32_e32 v17, v21, v21
	v_add_f32_e32 v26, v26, v27
	v_mul_f32_e32 v27, v33, v33
	v_and_b32_e32 v32, 0xffff0000, v83
	v_add_f32_e32 v16, v16, v17
	v_mul_f32_e32 v17, v29, v29
	v_fmac_f32_e32 v27, v31, v31
	v_lshlrev_b32_e32 v30, 16, v83
	v_fmac_f32_e32 v32, 0.5, v19
	v_fmac_f32_e32 v17, v23, v23
	v_add_f32_e32 v26, v27, v26
	v_mul_f32_e32 v27, v35, v35
	v_fmac_f32_e32 v30, 0.5, v18
	v_add_f32_e32 v16, v17, v16
	v_mul_f32_e32 v17, v32, v32
	v_fmac_f32_e32 v27, v34, v34
	v_fmac_f32_e32 v17, v30, v30
	v_add_f32_e32 v26, v27, v26
	v_add_f32_e32 v16, v17, v16
	v_add_f32_e32 v16, v26, v16
	ds_bpermute_b32 v17, v124, v16
	v_cvt_pk_bf16_f32 v26, v31, v33
	v_cvt_pk_bf16_f32 v27, v34, v35
	global_store_dwordx4 v[90:91], v[24:27], off
	v_cvt_pk_bf16_f32 v18, v28, v20
	s_waitcnt lgkmcnt(0)
	v_add_f32_e32 v16, v16, v17
	ds_bpermute_b32 v17, v125, v16
	v_cvt_pk_bf16_f32 v19, v21, v22
	v_cvt_pk_bf16_f32 v20, v23, v29
	v_cvt_pk_bf16_f32 v21, v30, v32
	global_store_dwordx4 v[90:91], v[18:21], off offset:256
	s_and_saveexec_b64 s[18:19], s[46:47]
	s_cbranch_execz .LBB0_318
	v_lshlrev_b64 v[18:19], 6, v[88:89]
	v_lshl_add_u64 v[18:19], s[28:29], 0, v[18:19]
	v_lshl_add_u64 v[18:19], s[60:61], 2, v[18:19]
	s_lshl_b32 s8, s78, 2
	v_lshl_add_u64 v[18:19], v[18:19], 0, s[8:9]
	s_waitcnt lgkmcnt(0)
	v_add_f32_e32 v16, v16, v17
	flat_store_dword v[18:19], v16
.LBB0_318:
	s_or_b64 exec, exec, s[18:19]
	s_waitcnt vmcnt(9)
	v_lshlrev_b32_e32 v16, 16, v68
	v_fmac_f32_e32 v16, 0.5, v12
	v_and_b32_e32 v12, 0xffff0000, v68
	v_fmac_f32_e32 v12, 0.5, v13
	v_lshlrev_b32_e32 v13, 16, v69
	v_fmac_f32_e32 v13, 0.5, v14
	v_and_b32_e32 v14, 0xffff0000, v69
	v_fmac_f32_e32 v14, 0.5, v15
	v_lshlrev_b32_e32 v15, 16, v70
	v_lshlrev_b32_e32 v18, 16, v71
	v_fmac_f32_e32 v15, 0.5, v8
	v_fmac_f32_e32 v18, 0.5, v10
	v_cvt_pk_bf16_f32 v8, v16, v12
	v_mul_f32_e32 v10, v12, v12
	v_lshlrev_b32_e32 v12, 16, v64
	v_fmac_f32_e32 v12, 0.5, v4
	v_and_b32_e32 v4, 0xffff0000, v64
	v_and_b32_e32 v19, 0xffff0000, v71
	v_fmac_f32_e32 v4, 0.5, v5
	v_lshlrev_b32_e32 v5, 16, v65
	s_waitcnt lgkmcnt(0)
	v_and_b32_e32 v17, 0xffff0000, v70
	v_fmac_f32_e32 v19, 0.5, v11
	v_mul_f32_e32 v11, v14, v14
	v_fmac_f32_e32 v5, 0.5, v6
	v_and_b32_e32 v6, 0xffff0000, v65
	v_fmac_f32_e32 v17, 0.5, v9
	v_cvt_pk_bf16_f32 v9, v13, v14
	v_fmac_f32_e32 v11, v13, v13
	v_fmac_f32_e32 v6, 0.5, v7
	v_lshlrev_b32_e32 v7, 16, v66
	v_and_b32_e32 v13, 0xffff0000, v66
	v_fmac_f32_e32 v7, 0.5, v0
	v_fmac_f32_e32 v13, 0.5, v1
	v_mul_f32_e32 v0, v4, v4
	v_mul_f32_e32 v1, v6, v6
	v_fmac_f32_e32 v10, v16, v16
	v_fmac_f32_e32 v0, v12, v12
	v_fmac_f32_e32 v1, v5, v5
	v_add_f32_e32 v10, v10, v11
	v_mul_f32_e32 v11, v17, v17
	v_and_b32_e32 v16, 0xffff0000, v67
	v_add_f32_e32 v0, v0, v1
	v_mul_f32_e32 v1, v13, v13
	v_fmac_f32_e32 v11, v15, v15
	v_lshlrev_b32_e32 v14, 16, v67
	v_fmac_f32_e32 v16, 0.5, v3
	v_fmac_f32_e32 v1, v7, v7
	v_add_f32_e32 v10, v11, v10
	v_mul_f32_e32 v11, v19, v19
	v_fmac_f32_e32 v14, 0.5, v2
	v_add_f32_e32 v0, v1, v0
	v_mul_f32_e32 v1, v16, v16
	v_fmac_f32_e32 v11, v18, v18
	v_fmac_f32_e32 v1, v14, v14
	v_add_f32_e32 v10, v11, v10
	v_add_f32_e32 v0, v1, v0
	v_add_f32_e32 v0, v10, v0
	ds_bpermute_b32 v1, v124, v0
	v_cvt_pk_bf16_f32 v10, v15, v17
	v_cvt_pk_bf16_f32 v11, v18, v19
	global_store_dwordx4 v[74:75], v[8:11], off
	v_cvt_pk_bf16_f32 v2, v12, v4
	s_waitcnt lgkmcnt(0)
	v_add_f32_e32 v0, v0, v1
	ds_bpermute_b32 v1, v125, v0
	v_cvt_pk_bf16_f32 v3, v5, v6
	v_cvt_pk_bf16_f32 v4, v7, v13
	v_cvt_pk_bf16_f32 v5, v14, v16
	global_store_dwordx4 v[74:75], v[2:5], off offset:256
	s_and_saveexec_b64 s[18:19], s[46:47]
	s_cbranch_execz .LBB0_320
	v_lshlrev_b64 v[2:3], 6, v[72:73]
	v_lshl_add_u64 v[2:3], s[28:29], 0, v[2:3]
	v_lshl_add_u64 v[2:3], s[60:61], 2, v[2:3]
	s_lshl_b32 s8, s78, 2
	v_lshl_add_u64 v[2:3], v[2:3], 0, s[8:9]
	s_waitcnt lgkmcnt(0)
	v_add_f32_e32 v0, v0, v1
	flat_store_dword v[2:3], v0

.LBB0_833:
	s_or_b64 exec, exec, s[62:63]
	v_or_b32_e32 v72, 48, v144
	v_ashrrev_i32_e32 v73, 31, v72
	s_waitcnt lgkmcnt(0)
	v_lshlrev_b64 v[64:65], 11, v[72:73]
	v_lshl_add_u64 v[64:65], s[26:27], 0, v[64:65]
	v_lshl_add_u64 v[74:75], v[182:183], 1, v[64:65]
	global_load_dwordx4 v[68:71], v[74:75], off
	global_load_dwordx4 v[64:67], v[74:75], off offset:256
	s_waitcnt vmcnt(15)
	v_lshlrev_b32_e32 v76, 16, v136
	v_add_f32_e32 v60, v60, v76
	v_and_b32_e32 v76, 0xffff0000, v136
	v_add_f32_e32 v61, v61, v76
	v_lshlrev_b32_e32 v76, 16, v137
	v_add_f32_e32 v62, v62, v76
	v_and_b32_e32 v76, 0xffff0000, v137
	v_add_f32_e32 v63, v63, v76
	v_lshlrev_b32_e32 v76, 16, v138
	v_add_f32_e32 v76, v56, v76
	v_and_b32_e32 v56, 0xffff0000, v138
	v_add_f32_e32 v77, v57, v56
	v_lshlrev_b32_e32 v56, 16, v139
	v_add_f32_e32 v78, v58, v56
	v_and_b32_e32 v56, 0xffff0000, v139
	v_mul_f32_e32 v58, v61, v61
	v_add_f32_e32 v59, v59, v56
	v_cvt_pk_bf16_f32 v56, v60, v61
	v_fmac_f32_e32 v58, v60, v60
	v_mul_f32_e32 v60, v63, v63
	v_fmac_f32_e32 v60, v62, v62
	v_add_f32_e32 v58, v58, v60
	v_mul_f32_e32 v60, v77, v77
	v_fmac_f32_e32 v60, v76, v76
	v_add_f32_e32 v58, v60, v58
	v_mul_f32_e32 v60, v59, v59
	v_fmac_f32_e32 v60, v78, v78
	v_add_f32_e32 v58, v60, v58
	v_lshlrev_b32_e32 v60, 16, v128
	v_add_f32_e32 v52, v52, v60
	v_and_b32_e32 v60, 0xffff0000, v128
	v_add_f32_e32 v53, v53, v60
	v_lshlrev_b32_e32 v60, 16, v129
	v_add_f32_e32 v54, v54, v60
	v_and_b32_e32 v60, 0xffff0000, v129
	v_add_f32_e32 v55, v55, v60
	v_lshlrev_b32_e32 v60, 16, v130
	v_add_f32_e32 v60, v48, v60
	v_and_b32_e32 v48, 0xffff0000, v130
	v_add_f32_e32 v61, v49, v48
	v_lshlrev_b32_e32 v48, 16, v131
	v_cvt_pk_bf16_f32 v57, v62, v63
	v_add_f32_e32 v62, v50, v48
	v_and_b32_e32 v48, 0xffff0000, v131
	v_add_f32_e32 v63, v51, v48
	v_mul_f32_e32 v48, v53, v53
	v_mul_f32_e32 v49, v55, v55
	v_fmac_f32_e32 v48, v52, v52
	v_fmac_f32_e32 v49, v54, v54
	v_add_f32_e32 v48, v48, v49
	v_mul_f32_e32 v49, v61, v61
	v_fmac_f32_e32 v49, v60, v60
	v_add_f32_e32 v48, v49, v48
	v_mul_f32_e32 v49, v63, v63
	v_fmac_f32_e32 v49, v62, v62
	v_add_f32_e32 v48, v49, v48
	v_add_f32_e32 v48, v58, v48
	ds_bpermute_b32 v49, v148, v48
	v_cvt_pk_bf16_f32 v58, v76, v77
	v_cvt_pk_bf16_f32 v59, v78, v59
	global_store_dwordx4 v[146:147], v[56:59], off
	v_cvt_pk_bf16_f32 v50, v52, v53
	s_waitcnt lgkmcnt(0)
	v_add_f32_e32 v48, v48, v49
	ds_bpermute_b32 v49, v149, v48
	v_cvt_pk_bf16_f32 v51, v54, v55
	v_cvt_pk_bf16_f32 v52, v60, v61
	v_cvt_pk_bf16_f32 v53, v62, v63
	global_store_dwordx4 v[146:147], v[50:53], off offset:256
	s_and_saveexec_b64 s[62:63], s[44:45]
	s_cbranch_execz .LBB0_835
	v_lshlrev_b64 v[50:51], 6, v[144:145]
	v_lshl_add_u64 v[50:51], s[28:29], 0, v[50:51]
	v_lshl_add_u64 v[50:51], s[60:61], 2, v[50:51]
	s_lshl_b32 s8, s76, 2
	v_lshl_add_u64 v[50:51], v[50:51], 0, s[8:9]
	s_waitcnt lgkmcnt(0)
	v_add_f32_e32 v48, v48, v49
	flat_store_dword v[50:51], v48
.LBB0_835:
	s_or_b64 exec, exec, s[62:63]
	s_waitcnt vmcnt(13)
	v_lshlrev_b32_e32 v48, 16, v100
	v_add_f32_e32 v44, v44, v48
	v_and_b32_e32 v48, 0xffff0000, v100
	v_add_f32_e32 v45, v45, v48
	v_lshlrev_b32_e32 v48, 16, v101
	v_add_f32_e32 v46, v46, v48
	v_and_b32_e32 v48, 0xffff0000, v101
	v_add_f32_e32 v47, v47, v48
	v_lshlrev_b32_e32 v48, 16, v102
	v_add_f32_e32 v48, v40, v48
	v_and_b32_e32 v40, 0xffff0000, v102
	s_waitcnt lgkmcnt(0)
	v_add_f32_e32 v49, v41, v40
	v_lshlrev_b32_e32 v40, 16, v103
	v_add_f32_e32 v50, v42, v40
	v_and_b32_e32 v40, 0xffff0000, v103
	v_mul_f32_e32 v42, v45, v45
	v_add_f32_e32 v43, v43, v40
	v_cvt_pk_bf16_f32 v40, v44, v45
	v_fmac_f32_e32 v42, v44, v44
	v_mul_f32_e32 v44, v47, v47
	v_fmac_f32_e32 v44, v46, v46
	v_add_f32_e32 v42, v42, v44
	v_mul_f32_e32 v44, v49, v49
	v_fmac_f32_e32 v44, v48, v48
	v_add_f32_e32 v42, v44, v42
	v_mul_f32_e32 v44, v43, v43
	v_fmac_f32_e32 v44, v50, v50
	v_add_f32_e32 v42, v44, v42
	v_lshlrev_b32_e32 v44, 16, v96
	v_add_f32_e32 v36, v36, v44
	v_and_b32_e32 v44, 0xffff0000, v96
	v_add_f32_e32 v37, v37, v44
	v_lshlrev_b32_e32 v44, 16, v97
	v_add_f32_e32 v38, v38, v44
	v_and_b32_e32 v44, 0xffff0000, v97
	v_add_f32_e32 v39, v39, v44
	v_lshlrev_b32_e32 v44, 16, v98
	v_add_f32_e32 v44, v32, v44
	v_and_b32_e32 v32, 0xffff0000, v98
	v_add_f32_e32 v45, v33, v32
	v_lshlrev_b32_e32 v32, 16, v99
	v_cvt_pk_bf16_f32 v41, v46, v47
	v_add_f32_e32 v46, v34, v32
	v_and_b32_e32 v32, 0xffff0000, v99
	v_add_f32_e32 v47, v35, v32
	v_mul_f32_e32 v32, v37, v37
	v_mul_f32_e32 v33, v39, v39
	v_fmac_f32_e32 v32, v36, v36
	v_fmac_f32_e32 v33, v38, v38
	v_add_f32_e32 v32, v32, v33
	v_mul_f32_e32 v33, v45, v45
	v_fmac_f32_e32 v33, v44, v44
	v_add_f32_e32 v32, v33, v32
	v_mul_f32_e32 v33, v47, v47
	v_fmac_f32_e32 v33, v46, v46
	v_add_f32_e32 v32, v33, v32
	v_add_f32_e32 v32, v42, v32
	ds_bpermute_b32 v33, v148, v32
	v_cvt_pk_bf16_f32 v42, v48, v49
	v_cvt_pk_bf16_f32 v43, v50, v43
	global_store_dwordx4 v[106:107], v[40:43], off
	v_cvt_pk_bf16_f32 v34, v36, v37
	s_waitcnt lgkmcnt(0)
	v_add_f32_e32 v32, v32, v33
	ds_bpermute_b32 v33, v149, v32
	v_cvt_pk_bf16_f32 v35, v38, v39
	v_cvt_pk_bf16_f32 v36, v44, v45
	v_cvt_pk_bf16_f32 v37, v46, v47
	global_store_dwordx4 v[106:107], v[34:37], off offset:256
	s_and_saveexec_b64 s[62:63], s[44:45]
	s_cbranch_execz .LBB0_837
	v_lshlrev_b64 v[34:35], 6, v[104:105]
	v_lshl_add_u64 v[34:35], s[28:29], 0, v[34:35]
	v_lshl_add_u64 v[34:35], s[60:61], 2, v[34:35]
	s_lshl_b32 s8, s76, 2
	v_lshl_add_u64 v[34:35], v[34:35], 0, s[8:9]
	s_waitcnt lgkmcnt(0)
	v_add_f32_e32 v32, v32, v33
	flat_store_dword v[34:35], v32
.LBB0_837:
	s_or_b64 exec, exec, s[62:63]
	s_waitcnt vmcnt(11)
	v_lshlrev_b32_e32 v32, 16, v84
	v_add_f32_e32 v28, v28, v32
	v_and_b32_e32 v32, 0xffff0000, v84
	v_add_f32_e32 v29, v29, v32
	v_lshlrev_b32_e32 v32, 16, v85
	v_add_f32_e32 v30, v30, v32
	v_and_b32_e32 v32, 0xffff0000, v85
	v_add_f32_e32 v31, v31, v32
	v_lshlrev_b32_e32 v32, 16, v86
	v_add_f32_e32 v32, v24, v32
	v_and_b32_e32 v24, 0xffff0000, v86
	s_waitcnt lgkmcnt(0)
	v_add_f32_e32 v33, v25, v24
	v_lshlrev_b32_e32 v24, 16, v87
	v_add_f32_e32 v34, v26, v24
	v_and_b32_e32 v24, 0xffff0000, v87
	v_mul_f32_e32 v26, v29, v29
	v_add_f32_e32 v27, v27, v24
	v_cvt_pk_bf16_f32 v24, v28, v29
	v_fmac_f32_e32 v26, v28, v28
	v_mul_f32_e32 v28, v31, v31
	v_fmac_f32_e32 v28, v30, v30
	v_add_f32_e32 v26, v26, v28
	v_mul_f32_e32 v28, v33, v33
	v_fmac_f32_e32 v28, v32, v32
	v_add_f32_e32 v26, v28, v26
	v_mul_f32_e32 v28, v27, v27
	v_fmac_f32_e32 v28, v34, v34
	v_add_f32_e32 v26, v28, v26
	v_lshlrev_b32_e32 v28, 16, v80
	v_add_f32_e32 v20, v20, v28
	v_and_b32_e32 v28, 0xffff0000, v80
	v_add_f32_e32 v21, v21, v28
	v_lshlrev_b32_e32 v28, 16, v81
	v_add_f32_e32 v22, v22, v28
	v_and_b32_e32 v28, 0xffff0000, v81
	v_add_f32_e32 v23, v23, v28
	v_lshlrev_b32_e32 v28, 16, v82
	v_add_f32_e32 v28, v16, v28
	v_and_b32_e32 v16, 0xffff0000, v82
	v_add_f32_e32 v29, v17, v16
	v_lshlrev_b32_e32 v16, 16, v83
	v_cvt_pk_bf16_f32 v25, v30, v31
	v_add_f32_e32 v30, v18, v16
	v_and_b32_e32 v16, 0xffff0000, v83
	v_add_f32_e32 v31, v19, v16
	v_mul_f32_e32 v16, v21, v21
	v_mul_f32_e32 v17, v23, v23
	v_fmac_f32_e32 v16, v20, v20
	v_fmac_f32_e32 v17, v22, v22
	v_add_f32_e32 v16, v16, v17
	v_mul_f32_e32 v17, v29, v29
	v_fmac_f32_e32 v17, v28, v28
	v_add_f32_e32 v16, v17, v16
	v_mul_f32_e32 v17, v31, v31
	v_fmac_f32_e32 v17, v30, v30
	v_add_f32_e32 v16, v17, v16
	v_add_f32_e32 v16, v26, v16
	ds_bpermute_b32 v17, v148, v16
	v_cvt_pk_bf16_f32 v26, v32, v33
	v_cvt_pk_bf16_f32 v27, v34, v27
	global_store_dwordx4 v[90:91], v[24:27], off
	v_cvt_pk_bf16_f32 v18, v20, v21
	s_waitcnt lgkmcnt(0)
	v_add_f32_e32 v16, v16, v17
	ds_bpermute_b32 v17, v149, v16
	v_cvt_pk_bf16_f32 v19, v22, v23
	v_cvt_pk_bf16_f32 v20, v28, v29
	v_cvt_pk_bf16_f32 v21, v30, v31
	global_store_dwordx4 v[90:91], v[18:21], off offset:256
	s_and_saveexec_b64 s[62:63], s[44:45]
	s_cbranch_execz .LBB0_839
	v_lshlrev_b64 v[18:19], 6, v[88:89]
	v_lshl_add_u64 v[18:19], s[28:29], 0, v[18:19]
	v_lshl_add_u64 v[18:19], s[60:61], 2, v[18:19]
	s_lshl_b32 s8, s76, 2
	v_lshl_add_u64 v[18:19], v[18:19], 0, s[8:9]
	s_waitcnt lgkmcnt(0)
	v_add_f32_e32 v16, v16, v17
	flat_store_dword v[18:19], v16
.LBB0_839:
	s_or_b64 exec, exec, s[62:63]
	s_waitcnt vmcnt(9)
	v_lshlrev_b32_e32 v16, 16, v68
	v_add_f32_e32 v12, v12, v16
	v_and_b32_e32 v16, 0xffff0000, v68
	v_add_f32_e32 v13, v13, v16
	v_lshlrev_b32_e32 v16, 16, v69
	v_add_f32_e32 v14, v14, v16
	v_and_b32_e32 v16, 0xffff0000, v69
	v_add_f32_e32 v15, v15, v16
	v_lshlrev_b32_e32 v16, 16, v70
	v_add_f32_e32 v16, v8, v16
	v_and_b32_e32 v8, 0xffff0000, v70
	s_waitcnt lgkmcnt(0)
	v_add_f32_e32 v17, v9, v8
	v_lshlrev_b32_e32 v8, 16, v71
	v_add_f32_e32 v18, v10, v8
	v_and_b32_e32 v8, 0xffff0000, v71
	v_mul_f32_e32 v10, v13, v13
	v_add_f32_e32 v11, v11, v8
	v_cvt_pk_bf16_f32 v8, v12, v13
	v_fmac_f32_e32 v10, v12, v12
	v_mul_f32_e32 v12, v15, v15
	v_fmac_f32_e32 v12, v14, v14
	v_add_f32_e32 v10, v10, v12
	v_mul_f32_e32 v12, v17, v17
	v_fmac_f32_e32 v12, v16, v16
	v_add_f32_e32 v10, v12, v10
	v_mul_f32_e32 v12, v11, v11
	v_fmac_f32_e32 v12, v18, v18
	v_add_f32_e32 v10, v12, v10
	v_lshlrev_b32_e32 v12, 16, v64
	v_add_f32_e32 v4, v4, v12
	v_and_b32_e32 v12, 0xffff0000, v64
	v_add_f32_e32 v5, v5, v12
	v_lshlrev_b32_e32 v12, 16, v65
	v_add_f32_e32 v6, v6, v12
	v_and_b32_e32 v12, 0xffff0000, v65
	v_add_f32_e32 v7, v7, v12
	v_lshlrev_b32_e32 v12, 16, v66
	v_add_f32_e32 v12, v0, v12
	v_and_b32_e32 v0, 0xffff0000, v66
	v_add_f32_e32 v13, v1, v0
	v_lshlrev_b32_e32 v0, 16, v67
	v_cvt_pk_bf16_f32 v9, v14, v15
	v_add_f32_e32 v14, v2, v0
	v_and_b32_e32 v0, 0xffff0000, v67
	v_add_f32_e32 v15, v3, v0
	v_mul_f32_e32 v0, v5, v5
	v_mul_f32_e32 v1, v7, v7
	v_fmac_f32_e32 v0, v4, v4
	v_fmac_f32_e32 v1, v6, v6
	v_add_f32_e32 v0, v0, v1
	v_mul_f32_e32 v1, v13, v13
	v_fmac_f32_e32 v1, v12, v12
	v_add_f32_e32 v0, v1, v0
	v_mul_f32_e32 v1, v15, v15
	v_fmac_f32_e32 v1, v14, v14
	v_add_f32_e32 v0, v1, v0
	v_add_f32_e32 v0, v10, v0
	ds_bpermute_b32 v1, v148, v0
	v_cvt_pk_bf16_f32 v10, v16, v17
	v_cvt_pk_bf16_f32 v11, v18, v11
	global_store_dwordx4 v[74:75], v[8:11], off
	v_cvt_pk_bf16_f32 v2, v4, v5
	s_waitcnt lgkmcnt(0)
	v_add_f32_e32 v0, v0, v1
	ds_bpermute_b32 v1, v149, v0
	v_cvt_pk_bf16_f32 v3, v6, v7
	v_cvt_pk_bf16_f32 v4, v12, v13
	v_cvt_pk_bf16_f32 v5, v14, v15
	global_store_dwordx4 v[74:75], v[2:5], off offset:256
	s_and_saveexec_b64 s[62:63], s[44:45]
	s_cbranch_execz .LBB0_841
	v_lshlrev_b64 v[2:3], 6, v[72:73]
	v_lshl_add_u64 v[2:3], s[28:29], 0, v[2:3]
	v_lshl_add_u64 v[2:3], s[60:61], 2, v[2:3]
	s_lshl_b32 s8, s76, 2
	v_lshl_add_u64 v[2:3], v[2:3], 0, s[8:9]
	s_waitcnt lgkmcnt(0)
	v_add_f32_e32 v0, v0, v1
	flat_store_dword v[2:3], v0
